# P0 rebalanced: waves that own a mods GEMV item skip weight transposes, the other waves take all transposes (stride NGW-1152); plus P0 transpose unroll and P3 epilogue
# speedup vs baseline: 1.0032x; 1.0032x over previous
; __device__ __forceinline__ void transpose_item(const float* W, int K, int N, bf16_t* WT, int dst0, int src0, int mode, int nblk, LAS float* scr, int item, int lane) {
;     const int kb = item / nblk, nb = item % nblk, k0 = 64 * kb, n0 = 32 * nb;
;     const int sc = srccol(mode, n0 + (lane & 31), src0);
; #pragma unroll 8
;     for (int i = 0; i < 32; ++i) { const int kk = 2 * i + (lane >> 5); scr[kk * 33 + (lane & 31)] = __builtin_nontemporal_load(W + (size_t)(k0 + kk) * N + sc); }
;     asm volatile("s_waitcnt lgkmcnt(0)" ::: "memory");
;     const int c = lane & 7;
; __global__ void __launch_bounds__(512, 2) fwd_megakernel(Args a_by_value) {
;     ...
;     if (ON(0)) for (int it = gw; it < 72 * 16; it += NGW) mods_item(a, mods, scr, it, lane);
;     if (ON(0)) {
;         constexpr int total = (D / 64) * (2 * FF / 32);
;         for (int it = gw; it < total; it += NGW) { int r = it; tj(a->w_gu1, D, 2 * FF, Wgu, 0, 2 * FF, 0, 2, r, scr, lane); }
.LBB0_27:
	s_cmpk_gt_i32 s30, 0x2bff
	v_lshrrev_b32_e32 v157, 3, v156
	v_lshlrev_b32_e32 v158, 3, v156
	s_cbranch_scc1 .LBB0_32
	s_sub_i32 s98, s34, 0x480
	s_mov_b32 s99, s30
	s_cmp_gt_i32 s98, 0
	s_cbranch_scc1 .Lp0_split
	s_mov_b32 s98, s34
	s_branch .Lp0_go
.Lp0_split:
	s_sub_i32 s99, s30, 0x480
	s_cmp_lt_i32 s99, 0
	s_cbranch_scc1 .LBB0_32
.Lp0_go:
	s_load_dwordx2 s[6:7], s[6:7], 0x38
	v_and_b32_e32 v0, 56, v158
	v_mul_u32_u24_e32 v2, 0x84, v0
	v_lshlrev_b32_e32 v3, 2, v157
	v_and_b32_e32 v18, 31, v162
	v_lshrrev_b32_e32 v19, 5, v156
	s_movk_i32 s8, 0x84
	v_lshlrev_b32_e32 v0, 1, v0
	v_mov_b32_e32 v1, 0
	v_add3_u32 v20, s41, v2, v3
	v_mov_b32_e32 v2, s33
	s_waitcnt lgkmcnt(0)
	v_lshl_add_u64 v[0:1], s[4:5], 0, v[0:1]
	s_mov_b64 s[4:5], 0x1700000
	v_mad_u32_u24 v2, v19, s8, v2
	v_lshlrev_b32_e32 v3, 2, v18
	v_lshl_add_u64 v[0:1], v[0:1], 0, s[4:5]
	v_or_b32_e32 v21, 8, v157
	v_or_b32_e32 v22, 16, v157
	v_or_b32_e32 v23, 24, v157
	v_add3_u32 v24, v2, v3, 0
	v_or_b32_e32 v25, 14, v19
	v_or_b32_e32 v26, 12, v19
	v_or_b32_e32 v27, 10, v19
	v_or_b32_e32 v28, 8, v19
	v_or_b32_e32 v29, 6, v19
	v_or_b32_e32 v30, 4, v19
	v_or_b32_e32 v31, 2, v19
	s_mov_b32 s10, 0xb000
	s_mov_b32 s11, s99

; #define LAS __attribute__((address_space(3)))
; __device__ __forceinline__ unsigned pk2(float lo, float hi) { return pg8::cvt_pk_bf16(lo, hi); }
; __device__ __forceinline__ void transpose_item(const float* W, int K, int N, bf16_t* WT, int dst0, int src0, int mode, int nblk, LAS float* scr, int item, int lane) {
;     ...
;     const int sc = srccol(mode, n0 + (lane & 31), src0);
; #pragma unroll 8
;     for (int i = 0; i < 32; ++i) { const int kk = 2 * i + (lane >> 5); scr[kk * 33 + (lane & 31)] = __builtin_nontemporal_load(W + (size_t)(k0 + kk) * N + sc); }
;     asm volatile("s_waitcnt lgkmcnt(0)" ::: "memory");
;     const int c = lane & 7;
; #pragma unroll
;     for (int j = 0; j < 4; ++j) { const int n = (lane >> 3) + 8 * j; const LAS float* s = scr + (8 * c) * 33 + n;
;         u32x4 o; o.x = pk2(s[0 * 33], s[1 * 33]); o.y = pk2(s[2 * 33], s[3 * 33]); o.z = pk2(s[4 * 33], s[5 * 33]); o.w = pk2(s[6 * 33], s[7 * 33]);
;         *(u32x4*)(WT + (size_t)(dst0 + n0 + n) * K + k0 + 8 * c) = o; }
;     asm volatile("s_waitcnt lgkmcnt(0)" ::: "memory");
.LBB0_30:
	v_lshl_add_u64 v[34:35], v[16:17], 0, s[8:9]
	v_lshl_add_u64 v[36:37], v[14:15], 0, s[8:9]
	v_lshl_add_u64 v[38:39], v[12:13], 0, s[8:9]
	v_lshl_add_u64 v[40:41], v[10:11], 0, s[8:9]
	v_lshl_add_u64 v[42:43], v[8:9], 0, s[8:9]
	v_lshl_add_u64 v[44:45], v[6:7], 0, s[8:9]
	v_lshl_add_u64 v[46:47], v[4:5], 0, s[8:9]
	v_lshl_add_u64 v[48:49], v[2:3], 0, s[8:9]
	global_load_dword v104, v[34:35], off nt
	global_load_dword v105, v[36:37], off nt
	global_load_dword v106, v[38:39], off nt
	global_load_dword v107, v[40:41], off nt
	global_load_dword v108, v[42:43], off nt
	global_load_dword v109, v[44:45], off nt
	global_load_dword v110, v[46:47], off nt
	global_load_dword v111, v[48:49], off nt
	s_add_u32 s8, s8, 0xb0000
	s_addc_u32 s9, s9, 0
	v_lshl_add_u64 v[34:35], v[16:17], 0, s[8:9]
	v_lshl_add_u64 v[36:37], v[14:15], 0, s[8:9]
	v_lshl_add_u64 v[38:39], v[12:13], 0, s[8:9]
	v_lshl_add_u64 v[40:41], v[10:11], 0, s[8:9]
	v_lshl_add_u64 v[42:43], v[8:9], 0, s[8:9]
	v_lshl_add_u64 v[44:45], v[6:7], 0, s[8:9]
	v_lshl_add_u64 v[46:47], v[4:5], 0, s[8:9]
	v_lshl_add_u64 v[48:49], v[2:3], 0, s[8:9]
	global_load_dword v112, v[34:35], off nt
	global_load_dword v113, v[36:37], off nt
	global_load_dword v114, v[38:39], off nt
	global_load_dword v115, v[40:41], off nt
	global_load_dword v116, v[42:43], off nt
	global_load_dword v117, v[44:45], off nt
	global_load_dword v118, v[46:47], off nt
	global_load_dword v119, v[48:49], off nt
	s_add_u32 s8, s8, 0xb0000
	s_addc_u32 s9, s9, 0
	v_lshl_add_u64 v[34:35], v[16:17], 0, s[8:9]
	v_lshl_add_u64 v[36:37], v[14:15], 0, s[8:9]
	v_lshl_add_u64 v[38:39], v[12:13], 0, s[8:9]
	v_lshl_add_u64 v[40:41], v[10:11], 0, s[8:9]
	v_lshl_add_u64 v[42:43], v[8:9], 0, s[8:9]
	v_lshl_add_u64 v[44:45], v[6:7], 0, s[8:9]
	v_lshl_add_u64 v[46:47], v[4:5], 0, s[8:9]
	v_lshl_add_u64 v[48:49], v[2:3], 0, s[8:9]
	global_load_dword v120, v[34:35], off nt
	global_load_dword v121, v[36:37], off nt
	global_load_dword v122, v[38:39], off nt
	global_load_dword v123, v[40:41], off nt
	global_load_dword v124, v[42:43], off nt
	global_load_dword v125, v[44:45], off nt
	global_load_dword v126, v[46:47], off nt
	global_load_dword v127, v[48:49], off nt
	s_add_u32 s8, s8, 0xb0000
	s_addc_u32 s9, s9, 0
	v_lshl_add_u64 v[34:35], v[16:17], 0, s[8:9]
	v_lshl_add_u64 v[36:37], v[14:15], 0, s[8:9]
	v_lshl_add_u64 v[38:39], v[12:13], 0, s[8:9]
	v_lshl_add_u64 v[40:41], v[10:11], 0, s[8:9]
	v_lshl_add_u64 v[42:43], v[8:9], 0, s[8:9]
	v_lshl_add_u64 v[44:45], v[6:7], 0, s[8:9]
	v_lshl_add_u64 v[46:47], v[4:5], 0, s[8:9]
	v_lshl_add_u64 v[48:49], v[2:3], 0, s[8:9]
	global_load_dword v128, v[34:35], off nt
	global_load_dword v129, v[36:37], off nt
	global_load_dword v130, v[38:39], off nt
	global_load_dword v131, v[40:41], off nt
	global_load_dword v132, v[42:43], off nt
	global_load_dword v133, v[44:45], off nt
	global_load_dword v134, v[46:47], off nt
	global_load_dword v135, v[48:49], off nt
	s_add_u32 s8, s8, 0xb0000
	s_addc_u32 s9, s9, 0
	v_add_u32_e32 v34, 0x400, v32
	s_waitcnt vmcnt(30)
	ds_write2_b32 v32, v104, v105 offset1:66
	s_waitcnt vmcnt(28)
	ds_write2_b32 v32, v106, v107 offset0:132 offset1:198
	s_waitcnt vmcnt(26)
	ds_write2_b32 v34, v108, v109 offset0:8 offset1:74
	s_waitcnt vmcnt(24)
	ds_write2_b32 v34, v110, v111 offset0:140 offset1:206
	v_add_u32_e32 v32, 0x840, v32
	v_add_u32_e32 v34, 0x400, v32
	s_waitcnt vmcnt(22)
	ds_write2_b32 v32, v112, v113 offset1:66
	s_waitcnt vmcnt(20)
	ds_write2_b32 v32, v114, v115 offset0:132 offset1:198
	s_waitcnt vmcnt(18)
	ds_write2_b32 v34, v116, v117 offset0:8 offset1:74
	s_waitcnt vmcnt(16)
	ds_write2_b32 v34, v118, v119 offset0:140 offset1:206
	v_add_u32_e32 v32, 0x840, v32
	v_add_u32_e32 v34, 0x400, v32
	s_waitcnt vmcnt(14)
	ds_write2_b32 v32, v120, v121 offset1:66
	s_waitcnt vmcnt(12)
	ds_write2_b32 v32, v122, v123 offset0:132 offset1:198
	s_waitcnt vmcnt(10)
	ds_write2_b32 v34, v124, v125 offset0:8 offset1:74
	s_waitcnt vmcnt(8)
	ds_write2_b32 v34, v126, v127 offset0:140 offset1:206
	v_add_u32_e32 v32, 0x840, v32
	v_add_u32_e32 v34, 0x400, v32
	s_waitcnt vmcnt(6)
	ds_write2_b32 v32, v128, v129 offset1:66
	s_waitcnt vmcnt(4)
	ds_write2_b32 v32, v130, v131 offset0:132 offset1:198
	s_waitcnt vmcnt(2)
	ds_write2_b32 v34, v132, v133 offset0:8 offset1:74
	s_waitcnt vmcnt(0)
	ds_write2_b32 v34, v134, v135 offset0:140 offset1:206
	v_add_u32_e32 v32, 0x840, v32
	s_cmp_lg_u32 s8, 0x2c0000
	s_waitcnt lgkmcnt(0)
	ds_read2_b32 v[6:7], v20 offset0:33 offset1:41
	ds_read2_b32 v[8:9], v20 offset1:8
	ds_read2_b32 v[10:11], v20 offset0:66 offset1:74
	ds_read2_b32 v[12:13], v20 offset0:99 offset1:107
	ds_read2_b32 v[14:15], v20 offset0:132 offset1:140
	ds_read2_b32 v[16:17], v20 offset0:165 offset1:173
	ds_read2_b32 v[32:33], v20 offset0:198 offset1:206
	ds_read2_b32 v[34:35], v20 offset0:231 offset1:239
	v_or_b32_e32 v38, s12, v157
	s_ashr_i32 s5, s4, 31
	v_ashrrev_i32_e32 v39, 31, v38
	v_lshl_add_u64 v[36:37], s[4:5], 1, v[0:1]
	v_lshlrev_b64 v[38:39], 12, v[38:39]
	s_waitcnt lgkmcnt(6)
	v_cvt_pk_bf16_f32 v2, v8, v6
	s_waitcnt lgkmcnt(4)
	v_cvt_pk_bf16_f32 v3, v10, v12
	s_waitcnt lgkmcnt(2)
	v_cvt_pk_bf16_f32 v4, v14, v16
	s_waitcnt lgkmcnt(0)
	v_cvt_pk_bf16_f32 v5, v32, v34
	v_lshl_add_u64 v[38:39], v[36:37], 0, v[38:39]
	v_or_b32_e32 v6, s12, v21
	global_store_dwordx4 v[38:39], v[2:5], off
	s_add_i32 s11, s11, s98
	s_cmpk_gt_i32 s11, 0x2bff
	v_cvt_pk_bf16_f32 v2, v9, v7
	v_ashrrev_i32_e32 v7, 31, v6
	v_cvt_pk_bf16_f32 v3, v11, v13
	v_cvt_pk_bf16_f32 v4, v15, v17
	v_cvt_pk_bf16_f32 v5, v33, v35
	v_lshlrev_b64 v[6:7], 12, v[6:7]
	ds_read2_b32 v[8:9], v20 offset0:49 offset1:57
	ds_read2_b32 v[10:11], v20 offset0:16 offset1:24
	ds_read2_b32 v[12:13], v20 offset0:82 offset1:90
	ds_read2_b32 v[14:15], v20 offset0:115 offset1:123
	ds_read2_b32 v[16:17], v20 offset0:148 offset1:156
	ds_read2_b32 v[32:33], v20 offset0:181 offset1:189
	ds_read2_b32 v[34:35], v20 offset0:214 offset1:222
	ds_read2_b32 v[38:39], v20 offset0:247 offset1:255
	v_lshl_add_u64 v[6:7], v[36:37], 0, v[6:7]
	global_store_dwordx4 v[6:7], v[2:5], off
	v_or_b32_e32 v6, s12, v22
	v_ashrrev_i32_e32 v7, 31, v6
	v_lshlrev_b64 v[6:7], 12, v[6:7]
	s_waitcnt lgkmcnt(6)
	v_cvt_pk_bf16_f32 v2, v10, v8
	s_waitcnt lgkmcnt(4)
	v_cvt_pk_bf16_f32 v3, v12, v14
	s_waitcnt lgkmcnt(2)
	v_cvt_pk_bf16_f32 v4, v16, v32
	s_waitcnt lgkmcnt(0)
	v_cvt_pk_bf16_f32 v5, v34, v38
	v_lshl_add_u64 v[6:7], v[36:37], 0, v[6:7]
	global_store_dwordx4 v[6:7], v[2:5], off
	v_or_b32_e32 v6, s12, v23
	v_ashrrev_i32_e32 v7, 31, v6
	v_lshlrev_b64 v[6:7], 12, v[6:7]
	v_cvt_pk_bf16_f32 v2, v11, v9
	v_cvt_pk_bf16_f32 v3, v13, v15
	v_cvt_pk_bf16_f32 v4, v17, v33
	v_cvt_pk_bf16_f32 v5, v35, v39
	v_lshl_add_u64 v[6:7], v[36:37], 0, v[6:7]
	global_store_dwordx4 v[6:7], v[2:5], off
	s_waitcnt lgkmcnt(0)
	s_cbranch_scc0 .LBB0_29

; __global__ void __launch_bounds__(512, 2) fwd_megakernel(Args a_by_value) {
	.amdhsa_kernel _Z14fwd_megakernel4Args
		.amdhsa_group_segment_fixed_size 0
		.amdhsa_private_segment_fixed_size 0
		.amdhsa_kernarg_size 448
		.amdhsa_user_sgpr_count 2
		.amdhsa_user_sgpr_dispatch_ptr 0
		.amdhsa_user_sgpr_queue_ptr 0
		.amdhsa_user_sgpr_kernarg_segment_ptr 1
		.amdhsa_user_sgpr_dispatch_id 0
		.amdhsa_user_sgpr_kernarg_preload_length 0
		.amdhsa_user_sgpr_kernarg_preload_offset 0
		.amdhsa_user_sgpr_private_segment_size 0
		.amdhsa_uses_dynamic_stack 0
		.amdhsa_enable_private_segment 0
		.amdhsa_system_sgpr_workgroup_id_x 1
		.amdhsa_system_sgpr_workgroup_id_y 0
		.amdhsa_system_sgpr_workgroup_id_z 0
		.amdhsa_system_sgpr_workgroup_info 0
		.amdhsa_system_vgpr_workitem_id 2
		.amdhsa_next_free_vgpr 253
		.amdhsa_next_free_sgpr 102
		.amdhsa_accum_offset 256
		.amdhsa_reserve_vcc 1
		.amdhsa_float_round_mode_32 0
		.amdhsa_float_round_mode_16_64 0
		.amdhsa_float_denorm_mode_32 3
		.amdhsa_float_denorm_mode_16_64 3
		.amdhsa_dx10_clamp 1
		.amdhsa_ieee_mode 1
		.amdhsa_fp16_overflow 0
		.amdhsa_tg_split 0
		.amdhsa_exception_fp_ieee_invalid_op 0
		.amdhsa_exception_fp_denorm_src 0
		.amdhsa_exception_fp_ieee_div_zero 0
		.amdhsa_exception_fp_ieee_overflow 0
		.amdhsa_exception_fp_ieee_underflow 0
		.amdhsa_exception_fp_ieee_inexact 0
		.amdhsa_exception_int_div_zero 0
	.end_amdhsa_kernel

; __global__ void __launch_bounds__(512, 2) fwd_megakernel(Args a_by_value) {
amdhsa.kernels:
  - .agpr_count:     0
    .args:
      - .offset:         0
        .size:           192
        .value_kind:     by_value
      - .offset:         192
        .size:           4
        .value_kind:     hidden_block_count_x
      - .offset:         196
        .size:           4
        .value_kind:     hidden_block_count_y
      - .offset:         200
        .size:           4
        .value_kind:     hidden_block_count_z
      - .offset:         204
        .size:           2
        .value_kind:     hidden_group_size_x
      - .offset:         206
        .size:           2
        .value_kind:     hidden_group_size_y
      - .offset:         208
        .size:           2
        .value_kind:     hidden_group_size_z
      - .offset:         210
        .size:           2
        .value_kind:     hidden_remainder_x
      - .offset:         212
        .size:           2
        .value_kind:     hidden_remainder_y
      - .offset:         214
        .size:           2
        .value_kind:     hidden_remainder_z
      - .offset:         232
        .size:           8
        .value_kind:     hidden_global_offset_x
      - .offset:         240
        .size:           8
        .value_kind:     hidden_global_offset_y
      - .offset:         248
        .size:           8
        .value_kind:     hidden_global_offset_z
      - .offset:         256
        .size:           2
        .value_kind:     hidden_grid_dims
      - .offset:         280
        .size:           8
        .value_kind:     hidden_multigrid_sync_arg
      - .offset:         312
        .size:           4
        .value_kind:     hidden_dynamic_lds_size
    .group_segment_fixed_size: 0
    .kernarg_segment_align: 8
    .kernarg_segment_size: 448
    .language:       OpenCL C
    .language_version:
      - 2
      - 0
    .max_flat_workgroup_size: 512
    .name:           _Z14fwd_megakernel4Args
    .private_segment_fixed_size: 0
    .sgpr_count:     108
    .sgpr_spill_count: 8
    .symbol:         _Z14fwd_megakernel4Args.kd
    .uniform_work_group_size: 1
    .uses_dynamic_stack: false
    .vgpr_count:     253
    .vgpr_spill_count: 0
    .wavefront_size: 64
